# v023: MLA attention loop-edge rotation as well (LDS read address setup hoisted to loop bottom, s12 as exit-compare temp)
# baseline (speedup 1.0000x reference)
; #define LAS __attribute__((address_space(3)))
; #define GAS __attribute__((address_space(1)))
; #define AT_LOAD(t) do { const GAS u32x4* Kg_ = (const GAS u32x4*)(Kp + (size_t)(t) * 128 * DK); const GAS u32x4* Vg_ = (const GAS u32x4*)(Vp + (size_t)(t) * 128 * 64); \
;         _Pragma("unroll") for (int i_ = 0; i_ < NKC; ++i_) kreg[i_] = Kg_[tid + 512 * i_]; vreg[0] = Vg_[tid]; vreg[1] = Vg_[tid + 512]; } while (0)
; #define AT_STORE(bf_) do { LAS unsigned char* nb_ = lds + (bf_) * AT_KBUF; _Pragma("unroll") for (int i_ = 0; i_ < NKC; ++i_) *(LAS u32x4*)(nb_ + koff[i_]) = kreg[i_]; \
;         *(LAS u32x4*)(lds + (bf_) * AT_VBUF + voff[0]) = vreg[0]; *(LAS u32x4*)(lds + (bf_) * AT_VBUF + voff[1]) = vreg[1]; } while (0)
; template <int DK>
; __device__ __forceinline__ void attn_unit(LAS unsigned char* lds, const GAS bf16* Qp, const GAS bf16* Kp, const GAS bf16* Vp, GAS bf16* Yp, int b, int j, int nkeys, int tid, int lane, int wave) {
;     constexpr int KSTR = DK * 2 + 16, ND = DK / 16, CPR = DK / 8, NKC = CPR / 4;
;     const int r32 = lane & 31, hi = lane >> 5;
;     bf16x8 qr[ND];
;     { const GAS bf16* Qw = Qp + (size_t)(256 * j + wave * 32 + r32) * DK + hi * 8;
; #pragma unroll
;       for (int d0 = 0; d0 < ND; ++d0) qr[d0] = *(const GAS bf16x8*)(Qw + d0 * 16); }
;     int koff[NKC], voff[2];
; #pragma unroll
;     for (int i = 0; i < NKC; ++i) { const int kc = tid + 512 * i; koff[i] = (kc / CPR) * KSTR + (kc % CPR) * 16; }
; #pragma unroll
;     for (int i = 0; i < 2; ++i) { const int vc = tid + 512 * i, vrow = vc >> 3, vch = vc & 7; voff[i] = AT_VOFF + (vch >> 2) * 8192 + (vrow >> 4) * 1024 + (vrow & 15) * 64 + (vch & 3) * 16; }
;     const int NT = nkeys >> 7;
;     u32x4 kreg[NKC], vreg[2];
;     ...
;     AT_LOAD(0); AT_STORE(0);
;     if (NT > 1) AT_LOAD(1);
;     __syncthreads();
;     LAS float* wsf = (LAS float*)(lds + AT_WSF) + wave * 32;
;     float mhat = 0.f;
;     f32x16 o0, o1, ol, negm;
; #pragma unroll
;     for (int r = 0; r < 16; ++r) { o0[r] = 0.f; o1[r] = 0.f; ol[r] = 0.f; negm[r] = 0.f; }
;     const bf16x8 ones = {0x3F80, 0x3F80, 0x3F80, 0x3F80, 0x3F80, 0x3F80, 0x3F80, 0x3F80};
;     const int kfo = r32 * KSTR + hi * 16;
;     const int vfo = AT_VOFF + (4 * hi + ((lane & 15) >> 2)) * 64 + ((lane >> 4) & 1) * 32 + (lane & 3) * 8;
.LBB0_132:
	s_andn2_b64 vcc, exec, s[22:23]
	s_cbranch_vccnz .LBB0_168
	s_mul_hi_i32 s73, s37, 0x2aaaaaab
	s_lshr_b32 s4, s73, 31
	s_add_i32 s73, s73, s4
	s_mul_i32 s4, s73, 6
	s_sub_i32 s74, s37, s4
	s_cmp_lg_u32 s24, 0
	s_cselect_b64 s[22:23], -1, 0
	s_cmp_eq_u32 s24, 0
	s_cselect_b64 s[44:45], -1, 0
	s_and_b64 s[4:5], s[44:45], exec
	s_movk_i32 s4, 0x100
	v_cmp_eq_u32_e32 vcc, 0, v0
	s_cselect_b32 s4, s4, 0x900
	s_mul_hi_i32 s5, s37, 0x48000
	s_mul_i32 s6, s37, 0x48000
	s_cbranch_vccnz .LBB0_151
	s_mul_i32 s10, s37, 0x6c000
	s_mul_hi_i32 s7, s37, 0x6c000
	s_add_u32 s8, s58, s10
	s_addc_u32 s9, s59, s7
	s_add_u32 s46, s60, s10
	s_addc_u32 s47, s61, s7
	s_add_u32 s48, s64, s6
	s_addc_u32 s49, s65, s5
	s_lshl_b32 s7, s24, 8
	v_readlane_b32 s10, v254, 2
	s_add_i32 s7, s7, s10
	v_or_b32_e32 v0, s7, v231
	v_mov_b64_e32 v[2:3], s[8:9]
	v_mad_i64_i32 v[2:3], s[8:9], v0, s76, v[2:3]
	v_lshl_add_u64 v[4:5], s[46:47], 0, v[206:207]
	s_movk_i32 s8, 0x2000
	v_add_co_u32_e32 v6, vcc, s8, v4
	v_lshl_add_u64 v[2:3], v[200:201], 1, v[2:3]
	s_nop 0
	v_addc_co_u32_e32 v7, vcc, 0, v5, vcc
	s_movk_i32 s9, 0x4000
	global_load_dwordx4 v[144:147], v[2:3], off
	global_load_dwordx4 v[148:151], v[2:3], off offset:32
	global_load_dwordx4 v[152:155], v[2:3], off offset:64
	global_load_dwordx4 v[156:159], v[2:3], off offset:96
	global_load_dwordx4 v[12:15], v[4:5], off
	global_load_dwordx4 v[16:19], v[6:7], off
	v_add_co_u32_e32 v6, vcc, s9, v4
	v_lshl_add_u64 v[8:9], s[48:49], 0, v[206:207]
	s_nop 0
	v_addc_co_u32_e32 v7, vcc, 0, v5, vcc
	global_load_dwordx4 v[20:23], v[6:7], off
	global_load_dwordx4 v[24:27], v[8:9], off
	v_add_co_u32_e32 v6, vcc, s8, v8
	s_movk_i32 s10, 0x6000
	s_nop 0
	v_addc_co_u32_e32 v7, vcc, 0, v9, vcc
	global_load_dwordx4 v[28:31], v[6:7], off
	v_add_co_u32_e32 v6, vcc, s10, v4
	s_mov_b32 s8, 0x8000
	s_nop 0
	v_addc_co_u32_e32 v7, vcc, 0, v5, vcc
	global_load_dwordx4 v[160:163], v[6:7], off
	v_add_co_u32_e32 v6, vcc, s8, v4
	s_mov_b32 s8, 0xa000
	s_nop 0
	v_addc_co_u32_e32 v7, vcc, 0, v5, vcc
	v_add_co_u32_e32 v4, vcc, s8, v4
	v_add_u32_e32 v32, 0, v234
	s_nop 0
	v_addc_co_u32_e32 v5, vcc, 0, v5, vcc
	global_load_dwordx4 v[164:167], v[6:7], off
	global_load_dwordx4 v[176:179], v[4:5], off
	v_add_co_u32_e32 v4, vcc, s9, v8
	v_mov_b32_e32 v0, v1
	s_nop 0
	v_addc_co_u32_e32 v5, vcc, 0, v9, vcc
	v_add_co_u32_e32 v6, vcc, s10, v8
	v_mov_b32_e32 v8, v1
	s_nop 0
	v_addc_co_u32_e32 v7, vcc, 0, v9, vcc
	global_load_dwordx4 v[180:183], v[4:5], off
	global_load_dwordx4 v[184:187], v[6:7], off
	global_load_dwordx4 v[168:171], v[2:3], off offset:128
	global_load_dwordx4 v[172:175], v[2:3], off offset:160
	v_mov_b32_e32 v2, v1
	v_mov_b32_e32 v3, v1
	v_mov_b32_e32 v4, v1
	v_mov_b32_e32 v5, v1
	v_mov_b32_e32 v6, v1
	v_mov_b32_e32 v7, v1
	v_mov_b32_e32 v9, v1
	v_mov_b32_e32 v10, v1
	v_mov_b32_e32 v11, v1
	s_lshr_b32 s8, s4, 7
	v_mov_b32_e32 v248, 0
	s_sub_i32 s9, 0, s8
	s_mov_b32 s10, 2
	v_mov_b32_e32 v64, 0
	v_mov_b32_e32 v65, v248
	v_mov_b32_e32 v66, v248
	v_mov_b32_e32 v67, v248
	v_mov_b32_e32 v68, v248
	v_mov_b32_e32 v69, v248
	v_mov_b32_e32 v70, v248
	v_mov_b32_e32 v71, v248
	v_mov_b32_e32 v72, v248
	v_mov_b32_e32 v73, v248
	v_mov_b32_e32 v74, v248
	v_mov_b32_e32 v75, v248
	v_mov_b32_e32 v76, v248
	v_mov_b32_e32 v77, v248
	v_mov_b32_e32 v78, v248
	v_mov_b32_e32 v79, v248
	s_waitcnt vmcnt(11)
	ds_write_b128 v246, v[12:15]
	s_waitcnt vmcnt(10)
	ds_write_b128 v247, v[16:19]
	s_waitcnt vmcnt(9)
	ds_write_b128 v32, v[20:23]
	s_waitcnt vmcnt(8)
	ds_write_b128 v245, v[24:27] offset:53248
	s_waitcnt vmcnt(7)
	ds_write_b128 v245, v[28:31] offset:57344
	v_mov_b32_e32 v14, v1
	v_mov_b32_e32 v15, v1
	v_mov_b32_e32 v12, v1
	v_mov_b32_e32 v13, v1
	v_mov_b64_e32 v[46:47], v[14:15]
	v_mov_b64_e32 v[30:31], v[14:15]
	v_mov_b64_e32 v[62:63], v[14:15]
	v_mov_b64_e32 v[44:45], v[12:13]
	v_mov_b64_e32 v[42:43], v[10:11]
	v_mov_b64_e32 v[40:41], v[8:9]
	v_mov_b64_e32 v[38:39], v[6:7]
	v_mov_b64_e32 v[36:37], v[4:5]
	v_mov_b64_e32 v[34:35], v[2:3]
	v_mov_b64_e32 v[32:33], v[0:1]
	v_mov_b64_e32 v[28:29], v[12:13]
	v_mov_b64_e32 v[26:27], v[10:11]
	v_mov_b64_e32 v[24:25], v[8:9]
	v_mov_b64_e32 v[22:23], v[6:7]
	v_mov_b64_e32 v[20:21], v[4:5]
	v_mov_b64_e32 v[18:19], v[2:3]
	v_mov_b64_e32 v[16:17], v[0:1]
	v_mov_b64_e32 v[60:61], v[12:13]
	v_mov_b64_e32 v[58:59], v[10:11]
	v_mov_b64_e32 v[56:57], v[8:9]
	v_mov_b64_e32 v[54:55], v[6:7]
	v_mov_b64_e32 v[52:53], v[4:5]
	v_mov_b64_e32 v[50:51], v[2:3]
	v_mov_b64_e32 v[48:49], v[0:1]
	s_add_i32 s11, s10, -2
	s_and_b32 s11, s11, 1
	s_mul_i32 s12, s11, 0x6800
	v_add_u32_e32 v0, s12, v237
	s_waitcnt lgkmcnt(0)
	s_barrier
	s_cmp_lt_u32 s97, 4
	s_cbranch_scc1 .Lprio_m
	s_setprio 1

; #define LAS __attribute__((address_space(3)))
; #define AT_PVK(ks, VF) do { o0 = __builtin_amdgcn_mfma_f32_32x32x16_bf16(__builtin_bit_cast(bf16x8, pw[ks]), VF[0], o0, 0, 0, 0); \
;             o1 = __builtin_amdgcn_mfma_f32_32x32x16_bf16(__builtin_bit_cast(bf16x8, pw[ks]), VF[1], o1, 0, 0, 0); \
;             ol = __builtin_amdgcn_mfma_f32_32x32x16_bf16(__builtin_bit_cast(bf16x8, pw[ks]), ones, ol, 0, 0, 0); } while (0)
; template <int DK>
; __device__ __forceinline__ void attn_unit(LAS unsigned char* lds, const GAS bf16* Qp, const GAS bf16* Kp, const GAS bf16* Vp, GAS bf16* Yp, int b, int j, int nkeys, int tid, int lane, int wave) {
;     ...
;         u32x4 pw[8];
;         { LAS unsigned char* vb = lds + cur * AT_VBUF + vfo;
;     ...
;           bf16x8 vfa[2], vfb[2];
;           vfa[0] = AT_VF(0, 0); vfa[1] = AT_VF(1, 0);
;           AT_EXPQ(0);
;           __builtin_amdgcn_sched_barrier(0);
; #pragma unroll
;           for (int q4 = 0; q4 < 4; ++q4) {
;               vfb[0] = AT_VF(0, 2 * q4 + 1); vfb[1] = AT_VF(1, 2 * q4 + 1);
;               AT_PVK(2 * q4, vfa);
;               if (q4 + 1 < 4) { AT_EXPQ(q4 + 1); vfa[0] = AT_VF(0, 2 * q4 + 2); vfa[1] = AT_VF(1, 2 * q4 + 2); }
;               AT_PVK(2 * q4 + 1, vfb);
;               __builtin_amdgcn_sched_barrier(0);
;           }
;     ...
;         }
;         __syncthreads();
.LBB0_136:
	v_lshl_add_u32 v0, s11, 14, v243
	ds_read_b64_tr_b16 v[2:3], v0 offset:53248
	ds_read_b64_tr_b16 v[4:5], v0 offset:53760
	ds_read_b64_tr_b16 v[6:7], v0 offset:61440
	ds_read_b64_tr_b16 v[8:9], v0 offset:61952
	v_exp_f32_e32 v10, v128
	v_exp_f32_e32 v11, v129
	v_exp_f32_e32 v12, v130
	v_exp_f32_e32 v13, v131
	v_exp_f32_e32 v15, v132
	v_exp_f32_e32 v128, v133
	v_exp_f32_e32 v129, v134
	v_exp_f32_e32 v130, v135
	v_exp_f32_e32 v131, v136
	v_exp_f32_e32 v132, v137
	v_exp_f32_e32 v133, v138
	v_exp_f32_e32 v134, v139
	v_exp_f32_e32 v135, v140
	v_exp_f32_e32 v136, v141
	v_exp_f32_e32 v137, v142
	v_exp_f32_e32 v138, v143
	v_add_u32_e32 v14, 0xd000, v0
	v_cvt_pk_bf16_f32 v10, v10, v11
	v_cvt_pk_bf16_f32 v11, v12, v13
	v_cvt_pk_bf16_f32 v12, v15, v128
	v_cvt_pk_bf16_f32 v13, v129, v130
	v_cvt_pk_bf16_f32 v128, v131, v132
	v_cvt_pk_bf16_f32 v129, v133, v134
	v_cvt_pk_bf16_f32 v130, v135, v136
	v_cvt_pk_bf16_f32 v131, v137, v138
	s_mov_b32 s69, s68
	s_waitcnt lgkmcnt(2)
	v_mfma_f32_32x32x16_bf16 v[32:47], v[10:13], v[2:5], v[32:47]
	s_mov_b32 s70, s68
	s_mov_b32 s71, s68
	v_mov_b64_e32 v[2:3], s[68:69]
	v_mov_b64_e32 v[4:5], s[70:71]
	v_exp_f32_e32 v15, v124
	ds_read_b64_tr_b16 v[132:133], v0 offset:54272
	ds_read_b64_tr_b16 v[134:135], v0 offset:54784
	s_waitcnt lgkmcnt(2)
	v_mfma_f32_32x32x16_bf16 v[16:31], v[10:13], v[6:9], v[16:31]
	v_exp_f32_e32 v6, v120
	v_exp_f32_e32 v7, v121
	v_exp_f32_e32 v8, v122
	v_exp_f32_e32 v9, v123
	v_exp_f32_e32 v120, v125
	v_exp_f32_e32 v121, v126
	v_cvt_pk_bf16_f32 v6, v6, v7
	v_mfma_f32_32x32x16_bf16 v[48:63], v[10:13], v[2:5], v[48:63]
	v_exp_f32_e32 v10, v127
	v_cvt_pk_bf16_f32 v7, v8, v9
	v_cvt_pk_bf16_f32 v8, v15, v120
	v_exp_f32_e32 v15, v112
	v_cvt_pk_bf16_f32 v9, v121, v10
	ds_read_b64_tr_b16 v[10:11], v0 offset:55296
	ds_read_b64_tr_b16 v[12:13], v0 offset:55808
	ds_read_b64_tr_b16 v[120:121], v0 offset:62464
	ds_read_b64_tr_b16 v[122:123], v0 offset:62976
	ds_read_b64_tr_b16 v[124:125], v0 offset:63488
	ds_read_b64_tr_b16 v[126:127], v0 offset:64000
	s_waitcnt lgkmcnt(6)
	v_mfma_f32_32x32x16_bf16 v[32:47], v[128:131], v[132:135], v[32:47]
	v_exp_f32_e32 v112, v113
	v_exp_f32_e32 v113, v114
	v_exp_f32_e32 v114, v115
	v_exp_f32_e32 v115, v116
	v_exp_f32_e32 v116, v117
	v_exp_f32_e32 v117, v118
	v_exp_f32_e32 v118, v119
	s_waitcnt lgkmcnt(2)
	v_mfma_f32_32x32x16_bf16 v[16:31], v[128:131], v[120:123], v[16:31]
	v_cvt_pk_bf16_f32 v112, v15, v112
	v_cvt_pk_bf16_f32 v113, v113, v114
	v_cvt_pk_bf16_f32 v114, v115, v116
	v_cvt_pk_bf16_f32 v115, v117, v118
	v_mfma_f32_32x32x16_bf16 v[48:63], v[128:131], v[2:5], v[48:63]
	s_nop 0
	v_mfma_f32_32x32x16_bf16 v[32:47], v[112:115], v[10:13], v[32:47]
	ds_read_b64_tr_b16 v[10:11], v0 offset:56320
	ds_read_b64_tr_b16 v[12:13], v0 offset:56832
	v_exp_f32_e32 v15, v104
	v_exp_f32_e32 v104, v105
	v_exp_f32_e32 v105, v106
	v_exp_f32_e32 v106, v107
	v_exp_f32_e32 v107, v108
	v_exp_f32_e32 v108, v109
	s_waitcnt lgkmcnt(2)
	v_mfma_f32_32x32x16_bf16 v[16:31], v[112:115], v[124:127], v[16:31]
	v_exp_f32_e32 v109, v110
	v_exp_f32_e32 v110, v111
	v_cvt_pk_bf16_f32 v105, v105, v106
	v_cvt_pk_bf16_f32 v106, v107, v108
	v_cvt_pk_bf16_f32 v104, v15, v104
	v_cvt_pk_bf16_f32 v107, v109, v110
	ds_read_b64_tr_b16 v[108:109], v0 offset:57344
	ds_read_b64_tr_b16 v[110:111], v0 offset:57856
	v_mfma_f32_32x32x16_bf16 v[48:63], v[112:115], v[2:5], v[48:63]
	v_exp_f32_e32 v15, v96
	v_exp_f32_e32 v96, v97
	v_exp_f32_e32 v97, v98
	v_exp_f32_e32 v98, v99
	v_exp_f32_e32 v99, v100
	v_exp_f32_e32 v100, v103
	s_waitcnt lgkmcnt(2)
	v_mfma_f32_32x32x16_bf16 v[32:47], v[6:9], v[10:13], v[32:47]
	ds_read_b64_tr_b16 v[10:11], v0 offset:64512
	ds_read_b64_tr_b16 v[12:13], v0 offset:65024
	ds_read_b64_tr_b16 v[112:113], v14 offset:12288
	ds_read_b64_tr_b16 v[114:115], v14 offset:12800
	s_waitcnt lgkmcnt(2)
	v_mfma_f32_32x32x16_bf16 v[16:31], v[6:9], v[10:13], v[16:31]
	v_exp_f32_e32 v12, v101
	v_exp_f32_e32 v13, v102
	v_cvt_pk_bf16_f32 v10, v15, v96
	v_cvt_pk_bf16_f32 v11, v97, v98
	v_cvt_pk_bf16_f32 v12, v99, v12
	v_cvt_pk_bf16_f32 v13, v13, v100
	v_mfma_f32_32x32x16_bf16 v[48:63], v[6:9], v[2:5], v[48:63]
	s_nop 0
	v_mfma_f32_32x32x16_bf16 v[32:47], v[10:13], v[108:111], v[32:47]
	ds_read_b64_tr_b16 v[6:7], v0 offset:58368
	ds_read_b64_tr_b16 v[8:9], v0 offset:58880
	v_exp_f32_e32 v15, v88
	v_exp_f32_e32 v88, v89
	v_exp_f32_e32 v89, v90
	v_exp_f32_e32 v90, v91
	v_exp_f32_e32 v91, v92
	v_exp_f32_e32 v92, v93
	s_waitcnt lgkmcnt(2)
	v_mfma_f32_32x32x16_bf16 v[16:31], v[10:13], v[112:115], v[16:31]
	v_exp_f32_e32 v93, v94
	v_mfma_f32_32x32x16_bf16 v[48:63], v[10:13], v[2:5], v[48:63]
	v_exp_f32_e32 v13, v95
	v_cvt_pk_bf16_f32 v10, v15, v88
	v_cvt_pk_bf16_f32 v11, v89, v90
	v_cvt_pk_bf16_f32 v12, v91, v92
	v_cvt_pk_bf16_f32 v13, v93, v13
	ds_read_b64_tr_b16 v[88:89], v0 offset:59392
	ds_read_b64_tr_b16 v[90:91], v0 offset:59904
	v_exp_f32_e32 v15, v80
	s_waitcnt lgkmcnt(2)
	v_mfma_f32_32x32x16_bf16 v[32:47], v[104:107], v[6:9], v[32:47]
	ds_read_b64_tr_b16 v[6:7], v14 offset:13312
	ds_read_b64_tr_b16 v[8:9], v14 offset:13824
	ds_read_b64_tr_b16 v[92:93], v14 offset:14336
	ds_read_b64_tr_b16 v[94:95], v14 offset:14848
	v_exp_f32_e32 v80, v81
	v_exp_f32_e32 v81, v82
	v_exp_f32_e32 v82, v83
	v_exp_f32_e32 v83, v84
	v_exp_f32_e32 v84, v87
	s_waitcnt lgkmcnt(2)
	v_mfma_f32_32x32x16_bf16 v[16:31], v[104:107], v[6:9], v[16:31]
	v_exp_f32_e32 v8, v85
	v_exp_f32_e32 v9, v86
	v_cvt_pk_bf16_f32 v6, v15, v80
	v_cvt_pk_bf16_f32 v7, v81, v82
	v_cvt_pk_bf16_f32 v8, v83, v8
	v_cvt_pk_bf16_f32 v9, v9, v84
	v_mfma_f32_32x32x16_bf16 v[48:63], v[104:107], v[2:5], v[48:63]
	s_nop 0
	v_mfma_f32_32x32x16_bf16 v[32:47], v[6:9], v[88:91], v[32:47]
	s_waitcnt lgkmcnt(0)
	v_mfma_f32_32x32x16_bf16 v[16:31], v[6:9], v[92:95], v[16:31]
	v_mfma_f32_32x32x16_bf16 v[48:63], v[6:9], v[2:5], v[48:63]
	ds_read_b64_tr_b16 v[6:7], v0 offset:60416
	ds_read_b64_tr_b16 v[8:9], v0 offset:60928
	ds_read_b64_tr_b16 v[80:81], v14 offset:15360
	ds_read_b64_tr_b16 v[82:83], v14 offset:15872
	s_waitcnt lgkmcnt(2)
	v_mfma_f32_32x32x16_bf16 v[32:47], v[10:13], v[6:9], v[32:47]
	s_waitcnt lgkmcnt(0)
	v_mfma_f32_32x32x16_bf16 v[16:31], v[10:13], v[80:83], v[16:31]
	v_mfma_f32_32x32x16_bf16 v[48:63], v[10:13], v[2:5], v[48:63]
	s_add_i32 s10, s10, 1
	s_add_u32 s48, s48, 0x4000
	s_addc_u32 s49, s49, 0
	s_add_u32 s46, s46, 0x6000
	s_addc_u32 s47, s47, 0
	s_add_i32 s11, s10, -2
	s_and_b32 s11, s11, 1
	s_mul_i32 s12, s11, 0x6800
	v_add_u32_e32 v0, s12, v237
	s_add_i32 s12, s9, s10
	s_cmp_lg_u32 s12, 2
	s_barrier
	s_cbranch_scc0 .LBB0_150
; #define LAS __attribute__((address_space(3)))
; #define AT_LOAD(t) do { const GAS u32x4* Kg_ = (const GAS u32x4*)(Kp + (size_t)(t) * 128 * DK); const GAS u32x4* Vg_ = (const GAS u32x4*)(Vp + (size_t)(t) * 128 * 64); \
;         _Pragma("unroll") for (int i_ = 0; i_ < NKC; ++i_) kreg[i_] = Kg_[tid + 512 * i_]; vreg[0] = Vg_[tid]; vreg[1] = Vg_[tid + 512]; } while (0)
; #define AT_STORE(bf_) do { LAS unsigned char* nb_ = lds + (bf_) * AT_KBUF; _Pragma("unroll") for (int i_ = 0; i_ < NKC; ++i_) *(LAS u32x4*)(nb_ + koff[i_]) = kreg[i_]; \
;         *(LAS u32x4*)(lds + (bf_) * AT_VBUF + voff[0]) = vreg[0]; *(LAS u32x4*)(lds + (bf_) * AT_VBUF + voff[1]) = vreg[1]; } while (0)
; template <int DK>
; __device__ __forceinline__ void attn_unit(LAS unsigned char* lds, const GAS bf16* Qp, const GAS bf16* Kp, const GAS bf16* Vp, GAS bf16* Yp, int b, int j, int nkeys, int tid, int lane, int wave) {
;     ...
;         { LAS unsigned char* kb = lds + cur * AT_KBUF + kfo;
;           bf16x8 ka[2][4];
; #pragma unroll
;           for (int q4 = 0; q4 < 4; ++q4) ka[0][q4] = *(LAS bf16x8*)(kb + q4 * 32 * KSTR);
; #pragma unroll
;           for (int d0 = 0; d0 < ND; ++d0) {
;               if (d0 + 1 < ND) {
; #pragma unroll
;                   for (int q4 = 0; q4 < 4; ++q4) ka[(d0 + 1) & 1][q4] = *(LAS bf16x8*)(kb + q4 * 32 * KSTR + (d0 + 1) * 32);
;               }
; #pragma unroll
;               for (int q4 = 0; q4 < 4; ++q4) p[q4] = __builtin_amdgcn_mfma_f32_32x32x16_bf16(ka[d0 & 1][q4], qr[d0], d0 == 0 ? negm : p[q4], 0, 0, 0);
;               if (d0 == 0) { if (t + 1 < NT) AT_STORE(cur ^ 1); if (t + 2 < NT) AT_LOAD(t + 2); }
.LBB0_137:
	ds_read_b128 v[6:9], v0
	ds_read_b128 v[2:5], v0 offset:32
	s_add_i32 s12, s10, -1
	s_cmp_ge_u32 s12, s8
	s_waitcnt lgkmcnt(1)
	v_mfma_f32_32x32x16_bf16 v[128:143], v[6:9], v[144:147], v[64:79]
	ds_read_b128 v[10:13], v0 offset:6656
	ds_read_b128 v[6:9], v0 offset:6688
	s_waitcnt lgkmcnt(1)
	v_mfma_f32_32x32x16_bf16 v[112:127], v[10:13], v[144:147], v[64:79]
	ds_read_b128 v[80:83], v0 offset:13312
	ds_read_b128 v[10:13], v0 offset:13344
	ds_read_b128 v[214:217], v0 offset:19968
	ds_read_b128 v[188:191], v0 offset:20000
	s_waitcnt lgkmcnt(3)
	v_mfma_f32_32x32x16_bf16 v[96:111], v[80:83], v[144:147], v[64:79]
	s_waitcnt lgkmcnt(1)
	v_mfma_f32_32x32x16_bf16 v[80:95], v[214:217], v[144:147], v[64:79]
	s_cbranch_scc1 .LBB0_139
	s_xor_b32 s12, s11, 1
	s_lshl_b32 s13, s12, 14
	s_add_i32 s13, s13, 0
	s_mulk_i32 s12, 0x2800
	v_add_u32_e32 v14, s13, v235
	s_add_i32 s13, s13, s12
	v_add_u32_e32 v15, s13, v232
	s_waitcnt vmcnt(6)
	ds_write_b128 v15, v[160:163]
	v_add_u32_e32 v15, s13, v233
	s_waitcnt vmcnt(5)
	ds_write_b128 v15, v[164:167]
	v_add_u32_e32 v15, s13, v234
	s_waitcnt vmcnt(4)
	ds_write_b128 v15, v[176:179]
	s_waitcnt vmcnt(3)
	ds_write_b128 v14, v[180:183] offset:53248
	s_waitcnt vmcnt(2)
	ds_write_b128 v14, v[184:187] offset:57344
